# RG-LRU finalize output stage: the four z loads issued together after the stage barrier, single vmcnt wait (groups no longer wait on the previous group's store)
# baseline (speedup 1.0000x reference)
; DI unsigned pack2(float a, float b) { f32v2 v = {a, b}; return __builtin_bit_cast(unsigned, __builtin_convertvector(v, bf16v2)); }
; DI float bflo(unsigned v) { return __uint_as_float(v << 16); }
; DI float bfhi(unsigned v) { return __uint_as_float(v & 0xffff0000u); }
; DI float silu(float x) { return x * sigm(x); }
; DI void lru_item(const Params& p, int l, int b, int chunk, int blk, bool fin, char* smem, int tid) {
;     ...
;   if (fin) {
;     __syncthreads();
;     const int ch4 = (tid & 15) * 4;
; #pragma unroll
;     for (int ps = 0; ps < 4; ps++) {
;       const int t = (tid >> 4) + 16 * ps;
;       const size_t row = (size_t)b * SEQA + pos0 + t;
;       uint2 zz = *(const uint2*)(p.Pk + row * PKW + 768 + 512 + c0 + ch4);
;       float y0 = au[(t) * 64 + ch4].y + au[(64 + t) * 64 + ch4].y, y1 = au[(t) * 64 + ch4 + 1].y + au[(64 + t) * 64 + ch4 + 1].y;
;       float y2 = au[(t) * 64 + ch4 + 2].y + au[(64 + t) * 64 + ch4 + 2].y, y3 = au[(t) * 64 + ch4 + 3].y + au[(64 + t) * 64 + ch4 + 3].y;
;       uint2 o; o.x = pack2(y0 * silu(bflo(zz.x)), y1 * silu(bfhi(zz.x))); o.y = pack2(y2 * silu(bflo(zz.y)), y3 * silu(bfhi(zz.y)));
;       *(uint2*)(p.G + row * 1024 + 512 + c0 + ch4) = o;
;     }
.Llf_scan_done:
.LBB0_1085:
	s_or_b64 exec, exec, s[0:1]
	v_ashrrev_i32_e32 v77, 31, v76
	s_movk_i32 s0, 0x1100
	v_mad_i64_i32 v[6:7], s[0:1], v73, s0, v[76:77]
	v_lshl_add_u64 v[8:9], v[6:7], 0, v[44:45]
	v_mov_b64_e32 v[4:5], s[90:91]
	v_mad_u64_u32 v[10:11], s[0:1], v8, s33, v[4:5]
	v_mad_i32_i24 v11, v9, s33, v11
	v_lshlrev_b64 v[2:3], 1, v[74:75]
	v_lshl_add_u64 v[10:11], v[10:11], 0, v[2:3]
	v_mov_b32_e32 v73, v1
	v_lshl_add_u64 v[10:11], v[10:11], 0, v[72:73]
	s_waitcnt lgkmcnt(0)
	s_barrier
	global_load_dwordx2 v[10:11], v[10:11], off offset:2560
	v_lshl_add_u64 v[122:123], v[6:7], 0, v[46:47]
	v_mad_u64_u32 v[124:125], s[0:1], v122, s33, v[4:5]
	v_mad_i32_i24 v125, v123, s33, v125
	v_lshl_add_u64 v[124:125], v[124:125], 0, v[2:3]
	v_lshl_add_u64 v[124:125], v[124:125], 0, v[72:73]
	global_load_dwordx2 v[124:125], v[124:125], off offset:2560
	v_lshl_add_u64 v[122:123], v[6:7], 0, v[48:49]
	v_mad_u64_u32 v[126:127], s[0:1], v122, s33, v[4:5]
	v_mad_i32_i24 v127, v123, s33, v127
	v_lshl_add_u64 v[126:127], v[126:127], 0, v[2:3]
	v_lshl_add_u64 v[126:127], v[126:127], 0, v[72:73]
	global_load_dwordx2 v[126:127], v[126:127], off offset:2560
	v_lshl_add_u64 v[122:123], v[6:7], 0, v[50:51]
	v_mad_u64_u32 v[128:129], s[0:1], v122, s33, v[4:5]
	v_mad_i32_i24 v129, v123, s33, v129
	v_lshl_add_u64 v[128:129], v[128:129], 0, v[2:3]
	v_lshl_add_u64 v[128:129], v[128:129], 0, v[72:73]
	global_load_dwordx2 v[128:129], v[128:129], off offset:2560
	v_add_u32_e32 v0, 0x2400, v90
	ds_read2_b32 v[12:13], v0 offset0:1 offset1:3
	ds_read2_b32 v[14:15], v0 offset0:5 offset1:7
	v_add_u32_e32 v0, 0xa400, v90
	ds_read2_b32 v[16:17], v0 offset0:1 offset1:3
	ds_read2_b32 v[18:19], v0 offset0:5 offset1:7
	v_readlane_b32 s2, v253, 48
	v_lshlrev_b64 v[8:9], 11, v[8:9]
	v_readlane_b32 s3, v253, 49
	s_waitcnt lgkmcnt(1)
	v_pk_add_f32 v[12:13], v[12:13], v[16:17]
	s_waitcnt lgkmcnt(0)
	v_pk_add_f32 v[14:15], v[14:15], v[18:19]
	v_lshl_add_u64 v[8:9], s[2:3], 0, v[8:9]
	v_lshl_add_u64 v[8:9], v[8:9], 0, v[2:3]
	v_lshl_add_u64 v[8:9], v[8:9], 0, v[72:73]
	s_waitcnt vmcnt(0)
	v_lshlrev_b32_e32 v20, 16, v10
	v_mul_f32_e32 v0, 0xbfb8aa3b, v20
	v_exp_f32_e32 v0, v0
	v_and_b32_e32 v21, 0xffff0000, v10
	v_add_f32_e32 v0, 1.0, v0
	v_rcp_f32_e32 v16, v0
	v_mul_f32_e32 v0, 0xbfb8aa3b, v21
	v_exp_f32_e32 v0, v0
	s_nop 0
	v_add_f32_e32 v0, 1.0, v0
	v_rcp_f32_e32 v17, v0
	s_nop 0
	v_pk_mul_f32 v[16:17], v[16:17], v[20:21]
	s_nop 0
	v_pk_mul_f32 v[12:13], v[12:13], v[16:17]
	s_nop 0
	v_cvt_pk_bf16_f32 v10, v12, v13
	v_lshlrev_b32_e32 v12, 16, v11
	v_mul_f32_e32 v0, 0xbfb8aa3b, v12
	v_exp_f32_e32 v0, v0
	v_and_b32_e32 v13, 0xffff0000, v11
	v_add_f32_e32 v0, 1.0, v0
	v_rcp_f32_e32 v16, v0
	v_mul_f32_e32 v0, 0xbfb8aa3b, v13
	v_exp_f32_e32 v0, v0
	s_nop 0
	v_add_f32_e32 v0, 1.0, v0
	v_rcp_f32_e32 v17, v0
	v_add_u32_e32 v0, 0x2400, v91
	v_pk_mul_f32 v[12:13], v[16:17], v[12:13]
	s_nop 0
	v_pk_mul_f32 v[12:13], v[14:15], v[12:13]
	s_nop 0
	v_cvt_pk_bf16_f32 v11, v12, v13
	global_store_dwordx2 v[8:9], v[10:11], off offset:1024
	v_lshl_add_u64 v[8:9], v[6:7], 0, v[46:47]
	ds_read2_b32 v[12:13], v0 offset0:1 offset1:3
	ds_read2_b32 v[14:15], v0 offset0:5 offset1:7
	v_add_u32_e32 v0, 0xa400, v91
	ds_read2_b32 v[16:17], v0 offset0:1 offset1:3
	ds_read2_b32 v[18:19], v0 offset0:5 offset1:7
	v_lshlrev_b64 v[8:9], 11, v[8:9]
	v_lshl_add_u64 v[8:9], s[2:3], 0, v[8:9]
	v_lshl_add_u64 v[8:9], v[8:9], 0, v[2:3]
	s_waitcnt lgkmcnt(1)
	v_pk_add_f32 v[12:13], v[12:13], v[16:17]
	s_waitcnt lgkmcnt(0)
; DI unsigned pack2(float a, float b) { f32v2 v = {a, b}; return __builtin_bit_cast(unsigned, __builtin_convertvector(v, bf16v2)); }
; DI float bflo(unsigned v) { return __uint_as_float(v << 16); }
; DI float bfhi(unsigned v) { return __uint_as_float(v & 0xffff0000u); }
; DI float silu(float x) { return x * sigm(x); }
; DI void lru_item(const Params& p, int l, int b, int chunk, int blk, bool fin, char* smem, int tid) {
;     ...
; #pragma unroll
;     for (int ps = 0; ps < 4; ps++) {
;       const int t = (tid >> 4) + 16 * ps;
;       const size_t row = (size_t)b * SEQA + pos0 + t;
;       uint2 zz = *(const uint2*)(p.Pk + row * PKW + 768 + 512 + c0 + ch4);
;       float y0 = au[(t) * 64 + ch4].y + au[(64 + t) * 64 + ch4].y, y1 = au[(t) * 64 + ch4 + 1].y + au[(64 + t) * 64 + ch4 + 1].y;
;       float y2 = au[(t) * 64 + ch4 + 2].y + au[(64 + t) * 64 + ch4 + 2].y, y3 = au[(t) * 64 + ch4 + 3].y + au[(64 + t) * 64 + ch4 + 3].y;
;       uint2 o; o.x = pack2(y0 * silu(bflo(zz.x)), y1 * silu(bfhi(zz.x))); o.y = pack2(y2 * silu(bflo(zz.y)), y3 * silu(bfhi(zz.y)));
;       *(uint2*)(p.G + row * 1024 + 512 + c0 + ch4) = o;
;     }
; DI void phase_mix(const Params& p, int l, char* smem, int tid) {
;     ...
;   for (int j = fetch_item(q + 256, smem); j < NLRU; j = fetch_item(q + 256, smem)) {
;     const int blk = j & 3;
;     int chunk, b;
;     if (need_ctx) { chunk = (j >> 2) % 68; b = (j >> 2) / 68; } else { chunk = 4 + ((j >> 2) & 63); b = (j >> 2) >> 6; }
;     lru_item(p, l, b, chunk, blk, true, smem, tid);
	v_pk_add_f32 v[14:15], v[14:15], v[18:19]
	v_lshl_add_u64 v[8:9], v[8:9], 0, v[72:73]
	v_lshlrev_b32_e32 v20, 16, v124
	v_mul_f32_e32 v0, 0xbfb8aa3b, v20
	v_exp_f32_e32 v0, v0
	v_and_b32_e32 v21, 0xffff0000, v124
	v_add_f32_e32 v0, 1.0, v0
	v_rcp_f32_e32 v16, v0
	v_mul_f32_e32 v0, 0xbfb8aa3b, v21
	v_exp_f32_e32 v0, v0
	s_nop 0
	v_add_f32_e32 v0, 1.0, v0
	v_rcp_f32_e32 v17, v0
	s_nop 0
	v_pk_mul_f32 v[16:17], v[16:17], v[20:21]
	s_nop 0
	v_pk_mul_f32 v[12:13], v[12:13], v[16:17]
	s_nop 0
	v_cvt_pk_bf16_f32 v10, v12, v13
	v_lshlrev_b32_e32 v12, 16, v125
	v_mul_f32_e32 v0, 0xbfb8aa3b, v12
	v_exp_f32_e32 v0, v0
	v_and_b32_e32 v13, 0xffff0000, v125
	v_add_f32_e32 v0, 1.0, v0
	v_rcp_f32_e32 v16, v0
	v_mul_f32_e32 v0, 0xbfb8aa3b, v13
	v_exp_f32_e32 v0, v0
	s_nop 0
	v_add_f32_e32 v0, 1.0, v0
	v_rcp_f32_e32 v17, v0
	v_add_u32_e32 v0, 0x2400, v92
	v_pk_mul_f32 v[12:13], v[16:17], v[12:13]
	s_nop 0
	v_pk_mul_f32 v[12:13], v[14:15], v[12:13]
	s_nop 0
	v_cvt_pk_bf16_f32 v11, v12, v13
	global_store_dwordx2 v[8:9], v[10:11], off offset:1024
	v_lshl_add_u64 v[8:9], v[6:7], 0, v[48:49]
	ds_read2_b32 v[12:13], v0 offset0:1 offset1:3
	ds_read2_b32 v[14:15], v0 offset0:5 offset1:7
	v_add_u32_e32 v0, 0xa400, v92
	ds_read2_b32 v[16:17], v0 offset0:1 offset1:3
	ds_read2_b32 v[18:19], v0 offset0:5 offset1:7
	v_lshlrev_b64 v[8:9], 11, v[8:9]
	v_lshl_add_u64 v[6:7], v[6:7], 0, v[50:51]
	v_lshl_add_u64 v[8:9], s[2:3], 0, v[8:9]
	s_waitcnt lgkmcnt(1)
	v_pk_add_f32 v[12:13], v[12:13], v[16:17]
	s_waitcnt lgkmcnt(0)
	v_pk_add_f32 v[14:15], v[14:15], v[18:19]
	v_lshl_add_u64 v[8:9], v[8:9], 0, v[2:3]
	v_lshl_add_u64 v[8:9], v[8:9], 0, v[72:73]
	v_lshlrev_b64 v[6:7], 11, v[6:7]
	v_lshl_add_u64 v[6:7], s[2:3], 0, v[6:7]
	v_lshl_add_u64 v[2:3], v[6:7], 0, v[2:3]
	v_lshl_add_u64 v[2:3], v[2:3], 0, v[72:73]
	v_lshlrev_b32_e32 v20, 16, v126
	v_mul_f32_e32 v0, 0xbfb8aa3b, v20
	v_exp_f32_e32 v0, v0
	v_and_b32_e32 v21, 0xffff0000, v126
	v_add_f32_e32 v0, 1.0, v0
	v_rcp_f32_e32 v16, v0
	v_mul_f32_e32 v0, 0xbfb8aa3b, v21
	v_exp_f32_e32 v0, v0
	s_nop 0
	v_add_f32_e32 v0, 1.0, v0
	v_rcp_f32_e32 v17, v0
	s_nop 0
	v_pk_mul_f32 v[16:17], v[16:17], v[20:21]
	s_nop 0
	v_pk_mul_f32 v[12:13], v[12:13], v[16:17]
	s_nop 0
	v_cvt_pk_bf16_f32 v10, v12, v13
	v_lshlrev_b32_e32 v12, 16, v127
	v_mul_f32_e32 v0, 0xbfb8aa3b, v12
	v_exp_f32_e32 v0, v0
	v_and_b32_e32 v13, 0xffff0000, v127
	v_add_f32_e32 v0, 1.0, v0
	v_rcp_f32_e32 v16, v0
	v_mul_f32_e32 v0, 0xbfb8aa3b, v13
	v_exp_f32_e32 v0, v0
	s_nop 0
	v_add_f32_e32 v0, 1.0, v0
	v_rcp_f32_e32 v17, v0
	v_add_u32_e32 v0, 0x2400, v93
	v_pk_mul_f32 v[12:13], v[16:17], v[12:13]
	s_nop 0
	v_pk_mul_f32 v[12:13], v[14:15], v[12:13]
	s_nop 0
	v_cvt_pk_bf16_f32 v11, v12, v13
	global_store_dwordx2 v[8:9], v[10:11], off offset:1024
	ds_read2_b32 v[8:9], v0 offset0:1 offset1:3
	ds_read2_b32 v[10:11], v0 offset0:5 offset1:7
	v_add_u32_e32 v0, 0xa400, v93
	ds_read2_b32 v[12:13], v0 offset0:1 offset1:3
	ds_read2_b32 v[14:15], v0 offset0:5 offset1:7
	s_waitcnt lgkmcnt(1)
	v_pk_add_f32 v[8:9], v[8:9], v[12:13]
	s_waitcnt lgkmcnt(0)
	v_pk_add_f32 v[10:11], v[10:11], v[14:15]
	v_lshlrev_b32_e32 v16, 16, v128
	v_mul_f32_e32 v0, 0xbfb8aa3b, v16
	v_exp_f32_e32 v0, v0
	v_and_b32_e32 v17, 0xffff0000, v128
	v_add_f32_e32 v0, 1.0, v0
	v_rcp_f32_e32 v12, v0
	v_mul_f32_e32 v0, 0xbfb8aa3b, v17
	v_exp_f32_e32 v0, v0
	s_nop 0
	v_add_f32_e32 v0, 1.0, v0
	v_rcp_f32_e32 v13, v0
	s_nop 0
	v_pk_mul_f32 v[12:13], v[12:13], v[16:17]
	s_nop 0
	v_pk_mul_f32 v[8:9], v[8:9], v[12:13]
	s_nop 0
	v_cvt_pk_bf16_f32 v4, v8, v9
	v_lshlrev_b32_e32 v8, 16, v129
	v_mul_f32_e32 v0, 0xbfb8aa3b, v8
	v_exp_f32_e32 v0, v0
	v_and_b32_e32 v9, 0xffff0000, v129
	v_add_f32_e32 v0, 1.0, v0
	v_rcp_f32_e32 v12, v0
	v_mul_f32_e32 v0, 0xbfb8aa3b, v9
	v_exp_f32_e32 v0, v0
	s_nop 0
	v_add_f32_e32 v0, 1.0, v0
	v_rcp_f32_e32 v13, v0
	s_nop 0
	v_pk_mul_f32 v[8:9], v[12:13], v[8:9]
	s_nop 0
	v_pk_mul_f32 v[8:9], v[10:11], v[8:9]
	s_nop 0
	v_cvt_pk_bf16_f32 v5, v8, v9
	global_store_dwordx2 v[2:3], v[4:5], off offset:1024
	s_barrier
	s_and_saveexec_b64 s[0:1], s[92:93]
	s_cbranch_execz .LBB0_1035
	s_mov_b64 s[12:13], exec
	v_mbcnt_lo_u32_b32 v0, s12, 0
	v_mbcnt_hi_u32_b32 v0, s13, v0
	v_cmp_eq_u32_e32 vcc, 0, v0
	s_and_saveexec_b64 s[2:3], vcc
	s_cbranch_execz .LBB0_1034
	s_bcnt1_i32_b64 s12, s[12:13]
	v_mov_b32_e32 v2, s12
	v_readlane_b32 s12, v254, 51
	v_readlane_b32 s13, v254, 52
	s_nop 4
	global_atomic_add v2, v1, v2, s[12:13] offset:1024 sc0
	s_branch .LBB0_1034
